# v44: output-projection row-sum exchanges use tagged 8-byte (value,tag) sc1 slots polled per wave: no store-ack wait, no counter atomic, one barrier less per exchange
# baseline (speedup 1.0000x reference)
.LBB0_628:
	s_or_b64 exec, exec, s[0:1]
	s_lshl_b32 s0, s11, 6
	s_add_i32 s28, s39, s0
	v_and_b32_e32 v0, 31, v146
	s_lshl_b32 s3, s28, 8
	v_lshl_or_b32 v226, s19, 5, v0
	v_add_u32_e32 v0, s3, v226
	s_waitcnt lgkmcnt(0)
	v_ashrrev_i32_e32 v1, 31, v0
	s_waitcnt lgkmcnt(0)
	s_barrier
	v_lshlrev_b64 v[0:1], 5, v[0:1]
	v_lshl_add_u64 v[174:175], s[16:17], 0, v[0:1]
	s_mov_b64 s[0:1], 0x9000000
	v_lshl_add_u64 v[0:1], v[174:175], 0, s[0:1]
	v_cmp_gt_u32_e64 s[4:5], 32, v132
	v_cmp_eq_u32_e64 s[8:9], 0, v132
	v_readlane_b32 s55, v255, 46
	s_lshl_b32 s34, s10, 6
	s_cmp_lt_u32 s2, 64
	s_cselect_b64 s[0:1], -1, 0
	s_lshr_b32 s11, s34, 5
	s_add_i32 s11, s11, 0x7fa5c301
	s_and_saveexec_b64 s[22:23], s[4:5]
	v_lshl_add_u32 v133, v226, 4, 16
	ds_read_b128 v[134:137], v133
	s_ashr_i32 s19, s18, 31
	s_waitcnt lgkmcnt(0)
	v_mov_b32_e32 v138, v135
	v_mov_b32_e32 v139, v136
	v_mov_b32_e32 v135, v137
	v_pk_add_f32 v[134:135], v[138:139], v[134:135]
	v_lshl_add_u64 v[136:137], s[18:19], 3, v[0:1]
	s_nop 0
	v_pk_add_f32 v[134:135], v[134:135], v[134:135] op_sel:[0,1] op_sel_hi:[1,0]
	s_nop 0
	v_mov_b32_e32 v135, s11
	global_store_dwordx2 v[136:137], v[134:135], off sc1
	s_mov_b32 s19, 0x100000
.Lxch1_poll:
	global_load_dwordx4 v[136:139], v[0:1], off sc1
	global_load_dwordx4 v[140:143], v[0:1], off offset:16 sc1
	s_waitcnt vmcnt(0)
	v_cmp_ne_u32_e32 vcc, s11, v137
	v_cmp_ne_u32_e64 s[24:25], s11, v139
	s_or_b64 s[24:25], s[24:25], vcc
	v_cmp_ne_u32_e32 vcc, s11, v141
	s_or_b64 s[24:25], s[24:25], vcc
	v_cmp_ne_u32_e32 vcc, s11, v143
	s_or_b64 s[24:25], s[24:25], vcc
	s_and_b64 s[24:25], s[24:25], exec
	s_cbranch_scc0 .Lxch1_done
	s_sub_i32 s19, s19, 1
	s_cmp_eq_u32 s19, 0
	s_cbranch_scc1 .Lxch1_done
	s_sleep 1
	s_branch .Lxch1_poll
.Lxch1_done:
	v_add_f32_e32 v133, 0, v136
	v_add_f32_e32 v133, v133, v138
	v_add_f32_e32 v133, v133, v140
	v_add_f32_e32 v133, v133, v142
	v_lshl_add_u32 v1, v226, 2, 16
	ds_write_b32 v1, v133 offset:4096
	s_or_b64 exec, exec, s[22:23]
	s_add_i32 s3, s3, s38
	s_lshl_b32 s11, s36, 5
	v_or_b32_e32 v168, s3, v3
	s_lshl_b32 s3, s18, 8
	s_or_b32 s3, s3, s11
	s_ashr_i32 s11, s10, 31
	s_lshl_b64 s[10:11], s[10:11], 12
	s_add_u32 s10, s12, s10
	s_addc_u32 s11, s13, s11
	s_add_u32 s24, s16, 0x5000000
	v_lshrrev_b32_e32 v227, 4, v132
	s_addc_u32 s25, s17, 0
	s_and_b32 s2, s2, 0xffffff00
	v_lshl_or_b32 v176, v227, 3, s3
	s_add_i32 s2, s2, 16
	v_lshl_add_u32 v0, v3, 2, s2
	v_ashrrev_i32_e32 v177, 31, v176
	v_ashrrev_i32_e32 v169, 31, v168
	v_or_b32_e32 v172, 16, v168
	v_add_u32_e32 v228, 0x1000, v0
	v_lshl_add_u64 v[140:141], v[176:177], 1, s[24:25]
	v_lshlrev_b64 v[0:1], 11, v[168:169]
	v_ashrrev_i32_e32 v173, 31, v172
	v_or_b32_e32 v170, 32, v168
	v_lshl_add_u64 v[180:181], v[140:141], 0, v[0:1]
	v_lshlrev_b64 v[0:1], 11, v[172:173]
	v_ashrrev_i32_e32 v171, 31, v170
	v_lshl_add_u64 v[182:183], v[140:141], 0, v[0:1]
	v_lshlrev_b64 v[0:1], 11, v[170:171]
	v_lshl_add_u64 v[184:185], v[140:141], 0, v[0:1]
	v_or_b32_e32 v0, 48, v168
	v_ashrrev_i32_e32 v1, 31, v0
	v_add_u32_e32 v212, 0x80, v168
	v_lshlrev_b64 v[142:143], 11, v[0:1]
	v_ashrrev_i32_e32 v213, 31, v212
	v_add_u32_e32 v210, 0x90, v168
	s_waitcnt vmcnt(0) lgkmcnt(0)
	s_barrier
	v_lshl_add_u64 v[186:187], v[140:141], 0, v[142:143]
	v_lshlrev_b64 v[142:143], 11, v[212:213]
	v_ashrrev_i32_e32 v211, 31, v210
	v_add_u32_e32 v206, 0xa0, v168
	ds_read2_b32 v[188:189], v228 offset1:16
	ds_read2_b32 v[214:215], v228 offset0:32 offset1:48
	ds_read2_b32 v[208:209], v228 offset0:128 offset1:144
	ds_read2_b32 v[202:203], v228 offset0:160 offset1:176
	s_waitcnt lgkmcnt(0)
	s_barrier
	v_lshl_add_u64 v[178:179], v[176:177], 2, s[10:11]
	v_lshl_add_u64 v[190:191], v[140:141], 0, v[142:143]
	v_lshlrev_b64 v[142:143], 11, v[210:211]
	v_ashrrev_i32_e32 v207, 31, v206
	v_add_u32_e32 v204, 0xb0, v168
	global_load_dwordx4 v[132:135], v[178:179], off offset:16
	global_load_dwordx4 v[136:139], v[178:179], off
	global_load_dwordx4 v[216:219], v[180:181], off
	global_load_dwordx4 v[164:167], v[182:183], off
	v_lshl_add_u64 v[192:193], v[140:141], 0, v[142:143]
	v_lshlrev_b64 v[142:143], 11, v[206:207]
	v_ashrrev_i32_e32 v205, 31, v204
	v_lshl_add_u64 v[194:195], v[140:141], 0, v[142:143]
	v_lshlrev_b64 v[142:143], 11, v[204:205]
	global_load_dwordx4 v[160:163], v[184:185], off
	global_load_dwordx4 v[156:159], v[186:187], off
	global_load_dwordx4 v[152:155], v[190:191], off
	global_load_dwordx4 v[148:151], v[192:193], off
	v_lshl_add_u64 v[196:197], v[140:141], 0, v[142:143]
	global_load_dwordx4 v[144:147], v[194:195], off
	global_load_dwordx4 v[140:143], v[196:197], off
	s_waitcnt lgkmcnt(0)
	v_fmamk_f32 v188, v188, 0x3a800000, v222
	v_mul_f32_e32 v198, 0x4f800000, v188
	v_cmp_gt_f32_e32 vcc, s73, v188
	s_cmp_eq_u64 s[20:21], 0
	s_cselect_b64 s[22:23], -1, 0
	v_cndmask_b32_e32 v188, v188, v198, vcc
	v_sqrt_f32_e32 v198, v188
	s_cmp_lg_u64 s[20:21], 0
	s_cselect_b64 s[12:13], -1, 0
	v_add_u32_e32 v199, -1, v198
	v_fma_f32 v200, -v199, v198, v188
	v_cmp_ge_f32_e64 s[10:11], 0, v200
	v_add_u32_e32 v200, 1, v198
	s_nop 0
	v_cndmask_b32_e64 v199, v198, v199, s[10:11]
	v_fma_f32 v198, -v200, v198, v188
	v_cmp_lt_f32_e64 s[10:11], 0, v198
	s_nop 1
	v_cndmask_b32_e64 v198, v199, v200, s[10:11]
	v_mul_f32_e32 v199, 0x37800000, v198
	v_cndmask_b32_e32 v198, v198, v199, vcc
	v_cmp_class_f32_e32 vcc, v188, v247
	s_mov_b64 s[10:11], -1
	s_nop 0
	v_cndmask_b32_e32 v188, v198, v188, vcc
	v_div_scale_f32 v198, s[2:3], v188, v188, 1.0
	v_rcp_f32_e32 v199, v198
	s_nop 0
	v_fma_f32 v200, -v198, v199, 1.0
	v_fmac_f32_e32 v199, v200, v199
	v_div_scale_f32 v200, vcc, 1.0, v188, 1.0
	v_mul_f32_e32 v201, v200, v199
	v_fma_f32 v220, -v198, v201, v200
	v_fmac_f32_e32 v201, v220, v199
	v_fma_f32 v198, -v198, v201, v200
	v_div_fmas_f32 v198, v198, v199, v201
	v_div_fixup_f32 v188, v198, v188, 1.0
	v_pk_mul_f32 v[128:129], v[128:129], v[188:189] op_sel_hi:[1,0]
	v_pk_mul_f32 v[130:131], v[130:131], v[188:189] op_sel_hi:[1,0]
	v_lshlrev_b64 v[200:201], 10, v[168:169]
	v_pk_mul_f32 v[124:125], v[124:125], v[188:189] op_sel_hi:[1,0]
	v_pk_mul_f32 v[126:127], v[126:127], v[188:189] op_sel_hi:[1,0]
	s_and_b64 vcc, exec, s[22:23]
	s_waitcnt vmcnt(0)
	v_lshlrev_b32_e32 v198, 16, v216
	v_and_b32_e32 v199, 0xffff0000, v216
	v_lshlrev_b32_e32 v216, 16, v217
	v_and_b32_e32 v217, 0xffff0000, v217
	v_pk_fma_f32 v[130:131], v[130:131], v[138:139], v[216:217]
	v_pk_fma_f32 v[128:129], v[128:129], v[136:137], v[198:199]
	v_lshlrev_b32_e32 v198, 16, v218
	v_and_b32_e32 v199, 0xffff0000, v218
	v_lshlrev_b32_e32 v216, 16, v219
	v_and_b32_e32 v217, 0xffff0000, v219
	v_pk_fma_f32 v[126:127], v[126:127], v[134:135], v[216:217]
	v_pk_fma_f32 v[124:125], v[124:125], v[132:133], v[198:199]
	v_lshl_add_u64 v[198:199], v[200:201], 2, s[20:21]
	s_cbranch_vccnz .LBB0_643
	v_lshl_add_u64 v[216:217], v[176:177], 2, v[198:199]
	s_mov_b64 s[10:11], 0
	global_store_dwordx4 v[216:217], v[128:131], off
	global_store_dwordx4 v[216:217], v[124:127], off offset:16

.LBB0_708:
	s_or_b64 exec, exec, s[10:11]
	s_waitcnt lgkmcnt(0)
	s_barrier
	s_mov_b64 s[2:3], 0x9100000
	v_lshl_add_u64 v[4:5], v[174:175], 0, s[2:3]
	s_lshr_b32 s2, s34, 5
	s_add_i32 s2, s2, 0x7fa5c302
	s_and_saveexec_b64 s[6:7], s[4:5]
	v_lshl_add_u32 v3, v226, 4, 16
	ds_read_b128 v[6:9], v3
	s_ashr_i32 s19, s18, 31
	s_waitcnt lgkmcnt(0)
	v_mov_b32_e32 v10, v7
	v_mov_b32_e32 v11, v8
	v_mov_b32_e32 v7, v9
	v_pk_add_f32 v[6:7], v[10:11], v[6:7]
	v_lshl_add_u64 v[8:9], s[18:19], 3, v[4:5]
	s_nop 0
	v_pk_add_f32 v[6:7], v[6:7], v[6:7] op_sel:[0,1] op_sel_hi:[1,0]
	s_nop 0
	v_mov_b32_e32 v7, s2
	global_store_dwordx2 v[8:9], v[6:7], off sc1
	s_mov_b32 s3, 0x100000
.Lxch2_poll:
	global_load_dwordx4 v[8:11], v[4:5], off sc1
	global_load_dwordx4 v[12:15], v[4:5], off offset:16 sc1
	s_waitcnt vmcnt(0)
	v_cmp_ne_u32_e32 vcc, s2, v9
	v_cmp_ne_u32_e64 s[0:1], s2, v11
	s_or_b64 s[0:1], s[0:1], vcc
	v_cmp_ne_u32_e32 vcc, s2, v13
	s_or_b64 s[0:1], s[0:1], vcc
	v_cmp_ne_u32_e32 vcc, s2, v15
	s_or_b64 s[0:1], s[0:1], vcc
	s_and_b64 s[0:1], s[0:1], exec
	s_cbranch_scc0 .Lxch2_done
	s_sub_i32 s3, s3, 1
	s_cmp_eq_u32 s3, 0
	s_cbranch_scc1 .Lxch2_done
	s_sleep 1
	s_branch .Lxch2_poll
.Lxch2_done:
	v_add_f32_e32 v3, 0, v8
	v_add_f32_e32 v3, v3, v10
	v_add_f32_e32 v3, v3, v12
	v_add_f32_e32 v3, v3, v14
	v_lshl_add_u32 v4, v226, 2, 16
	ds_write_b32 v4, v3 offset:4096
	s_or_b64 exec, exec, s[6:7]
	s_waitcnt vmcnt(0) lgkmcnt(0)
	s_barrier
	s_waitcnt lgkmcnt(4)
	ds_read2_b32 v[10:11], v228 offset1:16
	ds_read2_b32 v[8:9], v228 offset0:32 offset1:48
	ds_read2_b32 v[6:7], v228 offset0:128 offset1:144
	ds_read2_b32 v[4:5], v228 offset0:160 offset1:176
	s_waitcnt lgkmcnt(0)
	s_barrier
	v_or_b32_e32 v3, s36, v227
	v_or_b32_e32 v3, s18, v3
	v_cmp_eq_u32_e32 vcc, 0, v3
	s_and_saveexec_b64 s[0:1], vcc
	s_cbranch_execz .LBB0_595
	s_waitcnt lgkmcnt(3)
	v_fmamk_f32 v3, v10, 0x3a800000, v222
	v_mul_f32_e32 v10, 0x4f800000, v3
	v_cmp_gt_f32_e32 vcc, s73, v3
	v_fmamk_f32 v11, v11, 0x3a800000, v222
	s_add_u32 s6, s16, 0x9800000
	v_cndmask_b32_e32 v3, v3, v10, vcc
	v_sqrt_f32_e32 v10, v3
	s_addc_u32 s7, s17, 0
	s_waitcnt lgkmcnt(2)
	v_fmamk_f32 v8, v8, 0x3a800000, v222
	v_fmamk_f32 v9, v9, 0x3a800000, v222
	v_add_u32_e32 v12, -1, v10
	v_fma_f32 v14, -v12, v10, v3
	v_add_u32_e32 v13, 1, v10
	v_cmp_ge_f32_e64 s[4:5], 0, v14
	s_waitcnt lgkmcnt(1)
	v_fmamk_f32 v6, v6, 0x3a800000, v222
	v_lshl_add_u64 v[0:1], v[0:1], 2, s[6:7]
	v_cndmask_b32_e64 v12, v10, v12, s[4:5]
	v_fma_f32 v10, -v13, v10, v3
	v_cmp_lt_f32_e64 s[4:5], 0, v10
	s_waitcnt lgkmcnt(0)
	v_fmamk_f32 v4, v4, 0x3a800000, v222
	v_cndmask_b32_e64 v10, v12, v13, s[4:5]
	v_mul_f32_e32 v12, 0x37800000, v10
	v_cndmask_b32_e32 v10, v10, v12, vcc
	v_cmp_class_f32_e32 vcc, v3, v247
	v_cmp_gt_f32_e64 s[4:5], s73, v11
	s_nop 0
	v_cndmask_b32_e32 v3, v10, v3, vcc
	v_div_scale_f32 v10, s[2:3], v3, v3, 1.0
	v_rcp_f32_e32 v12, v10
	s_nop 0
	v_fma_f32 v13, -v10, v12, 1.0
	v_fmac_f32_e32 v12, v13, v12
	v_div_scale_f32 v13, vcc, 1.0, v3, 1.0
	v_mul_f32_e32 v14, v13, v12
	v_fma_f32 v15, -v10, v14, v13
	v_fmac_f32_e32 v14, v15, v12
	v_mul_f32_e32 v15, 0x4f800000, v11
	v_cndmask_b32_e64 v11, v11, v15, s[4:5]
	v_sqrt_f32_e32 v15, v11
	v_fma_f32 v10, -v10, v14, v13
	v_div_fmas_f32 v10, v10, v12, v14
	v_div_fixup_f32 v3, v10, v3, 1.0
	v_add_u32_e32 v12, -1, v15
	v_fma_f32 v13, -v12, v15, v11
	v_cmp_ge_f32_e32 vcc, 0, v13
	v_add_u32_e32 v13, 1, v15
	v_fma_f32 v14, -v13, v15, v11
	v_cndmask_b32_e32 v12, v15, v12, vcc
	v_cmp_lt_f32_e32 vcc, 0, v14
	s_nop 1
	v_cndmask_b32_e32 v12, v12, v13, vcc
	v_mul_f32_e32 v13, 0x37800000, v12
	v_cndmask_b32_e64 v12, v12, v13, s[4:5]
	v_cmp_class_f32_e32 vcc, v11, v247
	v_cmp_gt_f32_e64 s[4:5], s73, v8
	s_nop 0
	v_cndmask_b32_e32 v12, v12, v11, vcc
	v_div_scale_f32 v13, s[2:3], v12, v12, 1.0
	v_rcp_f32_e32 v14, v13
	v_lshl_add_u64 v[10:11], v[168:169], 2, s[6:7]
	global_store_dword v[10:11], v3, off
	v_fma_f32 v3, -v13, v14, 1.0
	v_fmac_f32_e32 v14, v3, v14
	v_div_scale_f32 v3, vcc, 1.0, v12, 1.0
	v_mul_f32_e32 v15, v3, v14
	v_fma_f32 v16, -v13, v15, v3
	v_fmac_f32_e32 v15, v16, v14
	v_mul_f32_e32 v16, 0x4f800000, v8
	v_cndmask_b32_e64 v8, v8, v16, s[4:5]
	v_sqrt_f32_e32 v16, v8
	v_fma_f32 v3, -v13, v15, v3
	v_div_fmas_f32 v3, v3, v14, v15
	v_div_fixup_f32 v3, v3, v12, 1.0
	v_add_u32_e32 v13, -1, v16
	v_fma_f32 v14, -v13, v16, v8
	v_cmp_ge_f32_e32 vcc, 0, v14
	v_add_u32_e32 v14, 1, v16
	v_fma_f32 v15, -v14, v16, v8
	v_cndmask_b32_e32 v13, v16, v13, vcc
	v_cmp_lt_f32_e32 vcc, 0, v15
	s_nop 1
	v_cndmask_b32_e32 v13, v13, v14, vcc
	v_mul_f32_e32 v14, 0x37800000, v13
	v_cndmask_b32_e64 v13, v13, v14, s[4:5]
	v_cmp_class_f32_e32 vcc, v8, v247
	v_cmp_gt_f32_e64 s[4:5], s73, v9
	s_nop 0
	v_cndmask_b32_e32 v8, v13, v8, vcc
	v_div_scale_f32 v14, s[2:3], v8, v8, 1.0
	v_rcp_f32_e32 v15, v14
	v_lshl_add_u64 v[12:13], v[172:173], 2, s[6:7]
	global_store_dword v[12:13], v3, off
	v_fma_f32 v3, -v14, v15, 1.0
	v_fmac_f32_e32 v15, v3, v15
	v_div_scale_f32 v3, vcc, 1.0, v8, 1.0
	v_mul_f32_e32 v12, v3, v15
	v_fma_f32 v13, -v14, v12, v3
	v_fmac_f32_e32 v12, v13, v15
	v_mul_f32_e32 v13, 0x4f800000, v9
	v_cndmask_b32_e64 v9, v9, v13, s[4:5]
	v_sqrt_f32_e32 v13, v9
	v_fma_f32 v3, -v14, v12, v3
	v_div_fmas_f32 v3, v3, v15, v12
	v_div_fixup_f32 v3, v3, v8, 1.0
	v_add_u32_e32 v12, -1, v13
	v_fma_f32 v14, -v12, v13, v9
	v_cmp_ge_f32_e32 vcc, 0, v14
	v_add_u32_e32 v14, 1, v13
	s_nop 0
	v_cndmask_b32_e32 v12, v13, v12, vcc
	v_fma_f32 v13, -v14, v13, v9
	v_cmp_lt_f32_e32 vcc, 0, v13
	s_nop 1
	v_cndmask_b32_e32 v12, v12, v14, vcc
	v_mul_f32_e32 v13, 0x37800000, v12
	v_cndmask_b32_e64 v12, v12, v13, s[4:5]
	v_cmp_class_f32_e32 vcc, v9, v247
	v_cmp_gt_f32_e64 s[4:5], s73, v6
	s_nop 0
	v_cndmask_b32_e32 v12, v12, v9, vcc
	v_div_scale_f32 v13, s[2:3], v12, v12, 1.0
	v_rcp_f32_e32 v14, v13
	v_lshl_add_u64 v[8:9], v[170:171], 2, s[6:7]
	global_store_dword v[8:9], v3, off
	v_fma_f32 v3, -v13, v14, 1.0
	v_fmac_f32_e32 v14, v3, v14
	v_div_scale_f32 v3, vcc, 1.0, v12, 1.0
	v_mul_f32_e32 v8, v3, v14
	v_fma_f32 v9, -v13, v8, v3
	v_fmac_f32_e32 v8, v9, v14
	v_mul_f32_e32 v9, 0x4f800000, v6
	v_cndmask_b32_e64 v6, v6, v9, s[4:5]
	v_sqrt_f32_e32 v9, v6
	v_fma_f32 v3, -v13, v8, v3
	v_div_fmas_f32 v3, v3, v14, v8
	v_div_fixup_f32 v3, v3, v12, 1.0
	v_add_u32_e32 v8, -1, v9
	v_fma_f32 v13, -v8, v9, v6
	v_cmp_ge_f32_e32 vcc, 0, v13
	v_add_u32_e32 v13, 1, v9
	global_store_dword v[0:1], v3, off
	v_cndmask_b32_e32 v8, v9, v8, vcc
	v_fma_f32 v9, -v13, v9, v6
	v_cmp_lt_f32_e32 vcc, 0, v9
	v_fmamk_f32 v3, v7, 0x3a800000, v222
	v_mul_f32_e32 v7, 0x4f800000, v3
	v_cndmask_b32_e32 v8, v8, v13, vcc
	v_mul_f32_e32 v9, 0x37800000, v8
	v_cndmask_b32_e64 v8, v8, v9, s[4:5]
	v_cmp_class_f32_e32 vcc, v6, v247
	v_cmp_gt_f32_e64 s[4:5], s73, v3
	s_nop 0
	v_cndmask_b32_e32 v6, v8, v6, vcc
	v_div_scale_f32 v8, s[2:3], v6, v6, 1.0
	v_rcp_f32_e32 v9, v8
	v_cndmask_b32_e64 v3, v3, v7, s[4:5]
	v_sqrt_f32_e32 v7, v3
	v_fma_f32 v0, -v8, v9, 1.0
	v_fmac_f32_e32 v9, v0, v9
	v_div_scale_f32 v0, vcc, 1.0, v6, 1.0
	v_mul_f32_e32 v1, v0, v9
	v_fma_f32 v12, -v8, v1, v0
	v_fmac_f32_e32 v1, v12, v9
	v_fma_f32 v0, -v8, v1, v0
	v_add_u32_e32 v8, -1, v7
	v_fma_f32 v12, -v8, v7, v3
	v_cmp_ge_f32_e64 s[6:7], 0, v12
	v_add_u32_e32 v12, 1, v7
	v_div_fmas_f32 v0, v0, v9, v1
	v_cndmask_b32_e64 v8, v7, v8, s[6:7]
	v_fma_f32 v7, -v12, v7, v3
	v_cmp_lt_f32_e64 s[6:7], 0, v7
	v_div_fixup_f32 v0, v0, v6, 1.0
	v_mul_f32_e32 v6, 0x4f800000, v4
	v_cndmask_b32_e64 v7, v8, v12, s[6:7]
	v_mul_f32_e32 v8, 0x37800000, v7
	v_cndmask_b32_e64 v7, v7, v8, s[4:5]
	v_cmp_class_f32_e64 s[4:5], v3, v247
	global_store_dword v[10:11], v0, off offset:512
	s_nop 0
	v_cndmask_b32_e64 v3, v7, v3, s[4:5]
	v_div_scale_f32 v7, s[2:3], v3, v3, 1.0
	v_rcp_f32_e32 v8, v7
	v_cmp_gt_f32_e64 s[4:5], s73, v4
	v_fma_f32 v0, -v7, v8, 1.0
	s_nop 0
	v_cndmask_b32_e64 v4, v4, v6, s[4:5]
	v_fmac_f32_e32 v8, v0, v8
	v_div_scale_f32 v0, vcc, 1.0, v3, 1.0
	v_sqrt_f32_e32 v6, v4
	v_mul_f32_e32 v1, v0, v8
	v_fma_f32 v9, -v7, v1, v0
	v_fmac_f32_e32 v1, v9, v8
	v_fma_f32 v0, -v7, v1, v0
	v_add_u32_e32 v7, -1, v6
	v_fma_f32 v9, -v7, v6, v4
	v_cmp_ge_f32_e64 s[6:7], 0, v9
	v_add_u32_e32 v9, 1, v6
	v_div_fmas_f32 v0, v0, v8, v1
	v_cndmask_b32_e64 v7, v6, v7, s[6:7]
	v_fma_f32 v6, -v9, v6, v4
	v_cmp_lt_f32_e64 s[6:7], 0, v6
	v_div_fixup_f32 v0, v0, v3, 1.0
	v_fmamk_f32 v3, v5, 0x3a800000, v222
	v_cndmask_b32_e64 v6, v7, v9, s[6:7]
	v_mul_f32_e32 v7, 0x37800000, v6
	v_cndmask_b32_e64 v6, v6, v7, s[4:5]
	v_cmp_class_f32_e64 s[4:5], v4, v247
	v_mul_f32_e32 v5, 0x4f800000, v3
	global_store_dword v[10:11], v0, off offset:576
	v_cndmask_b32_e64 v4, v6, v4, s[4:5]
	v_div_scale_f32 v6, s[2:3], v4, v4, 1.0
	v_rcp_f32_e32 v7, v6
	v_cmp_gt_f32_e64 s[4:5], s73, v3
	v_fma_f32 v0, -v6, v7, 1.0
	s_nop 0
	v_cndmask_b32_e64 v3, v3, v5, s[4:5]
	v_fmac_f32_e32 v7, v0, v7
	v_div_scale_f32 v0, vcc, 1.0, v4, 1.0
	v_sqrt_f32_e32 v5, v3
	v_mul_f32_e32 v1, v0, v7
	v_fma_f32 v8, -v6, v1, v0
	v_fmac_f32_e32 v1, v8, v7
	v_fma_f32 v0, -v6, v1, v0
	v_add_u32_e32 v6, -1, v5
	v_fma_f32 v8, -v6, v5, v3
	v_cmp_ge_f32_e64 s[6:7], 0, v8
	v_add_u32_e32 v8, 1, v5
	v_div_fmas_f32 v0, v0, v7, v1
	v_cndmask_b32_e64 v6, v5, v6, s[6:7]
	v_fma_f32 v5, -v8, v5, v3
	v_cmp_lt_f32_e64 s[6:7], 0, v5
	v_div_fixup_f32 v0, v0, v4, 1.0
	global_store_dword v[10:11], v0, off offset:640
	v_cndmask_b32_e64 v5, v6, v8, s[6:7]
	v_mul_f32_e32 v6, 0x37800000, v5
	v_cndmask_b32_e64 v5, v5, v6, s[4:5]
	v_cmp_class_f32_e64 s[4:5], v3, v247
	s_nop 1
	v_cndmask_b32_e64 v3, v5, v3, s[4:5]
	v_div_scale_f32 v5, s[2:3], v3, v3, 1.0
	v_rcp_f32_e32 v6, v5
	s_nop 0
	v_fma_f32 v0, -v5, v6, 1.0
	v_fmac_f32_e32 v6, v0, v6
	v_div_scale_f32 v0, vcc, 1.0, v3, 1.0
	v_mul_f32_e32 v1, v0, v6
	v_fma_f32 v4, -v5, v1, v0
	v_fmac_f32_e32 v1, v4, v6
	v_fma_f32 v0, -v5, v1, v0
	v_div_fmas_f32 v0, v0, v6, v1
	v_div_fixup_f32 v0, v0, v3, 1.0
	global_store_dword v[10:11], v0, off offset:704
	s_branch .LBB0_595
